# A (P5 rotation 4/group + P2/P10 spread) + SwiGLU epilogues: scalar mul/add pairs merged into v_pk_mul_f32/v_pk_add_f32
# speedup vs baseline: 1.0085x; 1.0085x over previous
.LBB0_240:
	s_mov_b32 s98, 0xbfb8aa3b
	s_mov_b32 s99, 0xbfb8aa3b
	v_mul_f32_e32 v151, 0xbfb8aa3b, v124
	v_exp_f32_e32 v151, v151
	v_mul_f32_e32 v153, 0xbfb8aa3b, v125
	v_exp_f32_e32 v155, v153
	v_lshl_or_b32 v152, s43, 7, v146
	v_add_f32_e32 v151, 1.0, v151
	v_rcp_f32_e32 v154, v151
	v_add_f32_e32 v151, 1.0, v155
	v_mul_f32_e32 v155, 0xbfb8aa3b, v126
	v_exp_f32_e32 v156, v155
	v_mul_f32_e32 v155, 0xbfb8aa3b, v127
	v_exp_f32_e32 v157, v155
	v_rcp_f32_e32 v155, v151
	v_add_f32_e32 v151, 1.0, v156
	v_rcp_f32_e32 v156, v151
	v_add_f32_e32 v151, 1.0, v157
	v_rcp_f32_e32 v157, v151
	v_mul_f32_e32 v151, 0xbfb8aa3b, v120
	v_pk_mul_f32 v[124:125], v[124:125], v[154:155]
	v_exp_f32_e32 v151, v151
	v_mul_f32_e32 v154, 0xbfb8aa3b, v121
	v_exp_f32_e32 v155, v154
	v_pk_mul_f32 v[126:127], v[126:127], v[156:157]
	v_add_f32_e32 v151, 1.0, v151
	v_rcp_f32_e32 v154, v151
	v_add_f32_e32 v151, 1.0, v155
	v_mul_f32_e32 v155, 0xbfb8aa3b, v122
	v_exp_f32_e32 v156, v155
	v_mul_f32_e32 v155, 0xbfb8aa3b, v123
	v_exp_f32_e32 v157, v155
	v_rcp_f32_e32 v155, v151
	v_add_f32_e32 v151, 1.0, v156
	v_rcp_f32_e32 v156, v151
	v_add_f32_e32 v151, 1.0, v157
	v_rcp_f32_e32 v157, v151
	v_pk_mul_f32 v[120:121], v[120:121], v[154:155]
	v_pk_mul_f32 v[118:119], v[126:127], v[118:119]
	v_pk_mul_f32 v[116:117], v[124:125], v[116:117]
	v_pk_mul_f32 v[122:123], v[122:123], v[156:157]
	v_pk_mul_f32 v[112:113], v[120:121], v[112:113]
	v_lshl_add_u32 v150, s18, 8, v144
	v_ashrrev_i32_e32 v153, 31, v152
	v_pk_mul_f32 v[114:115], v[122:123], v[114:115]
	v_cvt_pk_bf16_f32 v116, v116, v117
	v_cvt_pk_bf16_f32 v117, v118, v119
	v_cvt_pk_bf16_f32 v118, v112, v113
	v_mov_b64_e32 v[112:113], s[80:81]
	v_cvt_pk_bf16_f32 v119, v114, v115
	v_mad_i64_i32 v[120:121], s[20:21], v150, s42, v[112:113]
	v_lshlrev_b64 v[114:115], 1, v[152:153]
	v_lshl_add_u64 v[120:121], v[120:121], 0, v[114:115]
	v_pk_mul_f32 v[122:123], v[108:109], s[98:99] op_sel_hi:[1,0]
	global_store_dwordx4 v[120:121], v[116:119], off
	v_exp_f32_e32 v122, v122
	v_exp_f32_e32 v123, v123
	v_pk_mul_f32 v[118:119], v[110:111], s[98:99] op_sel_hi:[1,0]
	v_exp_f32_e32 v118, v118
	v_exp_f32_e32 v119, v119
	v_pk_add_f32 v[116:117], v[122:123], 1.0 op_sel_hi:[1,0]
	v_pk_add_f32 v[118:119], v[118:119], 1.0 op_sel_hi:[1,0]
	v_rcp_f32_e32 v116, v116
	v_rcp_f32_e32 v117, v117
	v_rcp_f32_e32 v118, v118
	v_rcp_f32_e32 v119, v119
	s_andn2_b64 vcc, exec, s[2:3]
	v_pk_mul_f32 v[108:109], v[108:109], v[116:117]
	v_pk_mul_f32 v[116:117], v[104:105], s[98:99] op_sel_hi:[1,0]
	v_pk_mul_f32 v[110:111], v[110:111], v[118:119]
	v_pk_mul_f32 v[118:119], v[106:107], s[98:99] op_sel_hi:[1,0]
	v_exp_f32_e32 v116, v116
	v_exp_f32_e32 v117, v117
	v_exp_f32_e32 v118, v118
	v_exp_f32_e32 v119, v119
	v_pk_add_f32 v[116:117], v[116:117], 1.0 op_sel_hi:[1,0]
	v_pk_add_f32 v[118:119], v[118:119], 1.0 op_sel_hi:[1,0]
	v_rcp_f32_e32 v116, v116
	v_rcp_f32_e32 v117, v117
	v_rcp_f32_e32 v118, v118
	v_rcp_f32_e32 v119, v119
	v_pk_mul_f32 v[100:101], v[108:109], v[100:101]
	v_pk_mul_f32 v[104:105], v[104:105], v[116:117]
	v_pk_mul_f32 v[102:103], v[110:111], v[102:103]
	v_pk_mul_f32 v[106:107], v[106:107], v[118:119]
	s_mov_b64 s[2:3], -1
	v_pk_mul_f32 v[106:107], v[106:107], v[98:99]
	v_pk_mul_f32 v[98:99], v[104:105], v[96:97]
	v_cvt_pk_bf16_f32 v96, v100, v101
	v_or_b32_e32 v100, 16, v150
	v_mad_i64_i32 v[100:101], s[20:21], v100, s42, v[112:113]
	v_cvt_pk_bf16_f32 v97, v102, v103
	v_cvt_pk_bf16_f32 v98, v98, v99
	v_cvt_pk_bf16_f32 v99, v106, v107
	v_lshl_add_u64 v[100:101], v[100:101], 0, v[114:115]
	v_pk_mul_f32 v[102:103], v[92:93], s[98:99] op_sel_hi:[1,0]
	global_store_dwordx4 v[100:101], v[96:99], off
	v_exp_f32_e32 v102, v102
	v_exp_f32_e32 v103, v103
	v_pk_mul_f32 v[98:99], v[94:95], s[98:99] op_sel_hi:[1,0]
	v_exp_f32_e32 v98, v98
	v_exp_f32_e32 v99, v99
	v_pk_add_f32 v[96:97], v[102:103], 1.0 op_sel_hi:[1,0]
	v_pk_add_f32 v[98:99], v[98:99], 1.0 op_sel_hi:[1,0]
	v_rcp_f32_e32 v96, v96
	v_rcp_f32_e32 v97, v97
	v_rcp_f32_e32 v98, v98
	v_rcp_f32_e32 v99, v99
	v_pk_mul_f32 v[92:93], v[92:93], v[96:97]
	v_pk_mul_f32 v[96:97], v[88:89], s[98:99] op_sel_hi:[1,0]
	v_pk_mul_f32 v[94:95], v[94:95], v[98:99]
	v_pk_mul_f32 v[98:99], v[90:91], s[98:99] op_sel_hi:[1,0]
	v_exp_f32_e32 v96, v96
	v_exp_f32_e32 v97, v97
	v_exp_f32_e32 v98, v98
	v_exp_f32_e32 v99, v99
	v_pk_add_f32 v[96:97], v[96:97], 1.0 op_sel_hi:[1,0]
	v_pk_add_f32 v[98:99], v[98:99], 1.0 op_sel_hi:[1,0]
	v_rcp_f32_e32 v96, v96
	v_rcp_f32_e32 v97, v97
	v_rcp_f32_e32 v98, v98
	v_rcp_f32_e32 v99, v99
	v_pk_mul_f32 v[84:85], v[92:93], v[84:85]
	v_pk_mul_f32 v[88:89], v[88:89], v[96:97]
	v_pk_mul_f32 v[86:87], v[94:95], v[86:87]
	v_pk_mul_f32 v[90:91], v[90:91], v[98:99]
	s_nop 0
	v_pk_mul_f32 v[90:91], v[90:91], v[82:83]
	v_pk_mul_f32 v[82:83], v[88:89], v[80:81]
	v_cvt_pk_bf16_f32 v80, v84, v85
	v_or_b32_e32 v84, 32, v150
	v_mad_i64_i32 v[84:85], s[20:21], v84, s42, v[112:113]
	v_cvt_pk_bf16_f32 v81, v86, v87
	v_cvt_pk_bf16_f32 v82, v82, v83
	v_cvt_pk_bf16_f32 v83, v90, v91
	v_lshl_add_u64 v[84:85], v[84:85], 0, v[114:115]
	v_pk_mul_f32 v[86:87], v[76:77], s[98:99] op_sel_hi:[1,0]
	global_store_dwordx4 v[84:85], v[80:83], off
	v_exp_f32_e32 v86, v86
	v_exp_f32_e32 v87, v87
	v_pk_mul_f32 v[82:83], v[78:79], s[98:99] op_sel_hi:[1,0]
	v_exp_f32_e32 v82, v82
	v_exp_f32_e32 v83, v83
	v_pk_add_f32 v[80:81], v[86:87], 1.0 op_sel_hi:[1,0]
	v_pk_add_f32 v[82:83], v[82:83], 1.0 op_sel_hi:[1,0]
	v_rcp_f32_e32 v80, v80
	v_rcp_f32_e32 v81, v81
	v_rcp_f32_e32 v82, v82
	v_rcp_f32_e32 v83, v83
	v_pk_mul_f32 v[76:77], v[76:77], v[80:81]
	v_pk_mul_f32 v[80:81], v[72:73], s[98:99] op_sel_hi:[1,0]
	v_pk_mul_f32 v[78:79], v[78:79], v[82:83]
	v_pk_mul_f32 v[82:83], v[74:75], s[98:99] op_sel_hi:[1,0]
	v_exp_f32_e32 v80, v80
	v_exp_f32_e32 v81, v81
	v_exp_f32_e32 v82, v82
	v_exp_f32_e32 v83, v83
	v_pk_add_f32 v[80:81], v[80:81], 1.0 op_sel_hi:[1,0]
	v_pk_add_f32 v[82:83], v[82:83], 1.0 op_sel_hi:[1,0]
	v_rcp_f32_e32 v80, v80
	v_rcp_f32_e32 v81, v81
	v_rcp_f32_e32 v82, v82
	v_rcp_f32_e32 v83, v83
	v_pk_mul_f32 v[68:69], v[76:77], v[68:69]
	v_pk_mul_f32 v[72:73], v[72:73], v[80:81]
	v_pk_mul_f32 v[70:71], v[78:79], v[70:71]
	v_pk_mul_f32 v[74:75], v[74:75], v[82:83]
	s_nop 0
	v_pk_mul_f32 v[74:75], v[74:75], v[66:67]
	v_pk_mul_f32 v[66:67], v[72:73], v[64:65]
	v_cvt_pk_bf16_f32 v64, v68, v69
	v_or_b32_e32 v68, 48, v150
	v_mad_i64_i32 v[68:69], s[20:21], v68, s42, v[112:113]
	v_cvt_pk_bf16_f32 v65, v70, v71
	v_cvt_pk_bf16_f32 v66, v66, v67
	v_cvt_pk_bf16_f32 v67, v74, v75
	v_lshl_add_u64 v[68:69], v[68:69], 0, v[114:115]
	global_store_dwordx4 v[68:69], v[64:67], off
	v_add_u32_e32 v68, 0x80, v150
	s_nop 0
	v_pk_mul_f32 v[64:65], v[60:61], s[98:99] op_sel_hi:[1,0]
	v_pk_mul_f32 v[66:67], v[62:63], s[98:99] op_sel_hi:[1,0]
	v_exp_f32_e32 v64, v64
	v_exp_f32_e32 v65, v65
	v_exp_f32_e32 v66, v66
	v_exp_f32_e32 v67, v67
	v_pk_add_f32 v[64:65], v[64:65], 1.0 op_sel_hi:[1,0]
	v_pk_add_f32 v[66:67], v[66:67], 1.0 op_sel_hi:[1,0]
	v_rcp_f32_e32 v64, v64
	v_rcp_f32_e32 v65, v65
	v_rcp_f32_e32 v66, v66
	v_rcp_f32_e32 v67, v67
	v_pk_mul_f32 v[60:61], v[60:61], v[64:65]
	v_pk_mul_f32 v[64:65], v[56:57], s[98:99] op_sel_hi:[1,0]
	v_pk_mul_f32 v[62:63], v[62:63], v[66:67]
	v_pk_mul_f32 v[66:67], v[58:59], s[98:99] op_sel_hi:[1,0]
	v_exp_f32_e32 v64, v64
	v_exp_f32_e32 v65, v65
	v_exp_f32_e32 v66, v66
	v_exp_f32_e32 v67, v67
	v_pk_add_f32 v[64:65], v[64:65], 1.0 op_sel_hi:[1,0]
	v_pk_add_f32 v[66:67], v[66:67], 1.0 op_sel_hi:[1,0]
	v_rcp_f32_e32 v64, v64
	v_rcp_f32_e32 v65, v65
	v_rcp_f32_e32 v66, v66
	v_rcp_f32_e32 v67, v67
	v_pk_mul_f32 v[52:53], v[60:61], v[52:53]
	v_pk_mul_f32 v[56:57], v[56:57], v[64:65]
	v_pk_mul_f32 v[54:55], v[62:63], v[54:55]
	v_pk_mul_f32 v[58:59], v[58:59], v[66:67]
	s_nop 0
	v_pk_mul_f32 v[58:59], v[58:59], v[50:51]
	v_pk_mul_f32 v[50:51], v[56:57], v[48:49]
	v_cvt_pk_bf16_f32 v48, v52, v53
	v_mad_i64_i32 v[52:53], s[20:21], v68, s42, v[112:113]
	v_cvt_pk_bf16_f32 v49, v54, v55
	v_cvt_pk_bf16_f32 v50, v50, v51
	v_cvt_pk_bf16_f32 v51, v58, v59
	v_lshl_add_u64 v[52:53], v[52:53], 0, v[114:115]
	v_pk_mul_f32 v[54:55], v[44:45], s[98:99] op_sel_hi:[1,0]
	global_store_dwordx4 v[52:53], v[48:51], off
	v_exp_f32_e32 v54, v54
	v_exp_f32_e32 v55, v55
	v_pk_mul_f32 v[50:51], v[46:47], s[98:99] op_sel_hi:[1,0]
	v_exp_f32_e32 v50, v50
	v_exp_f32_e32 v51, v51
	v_pk_add_f32 v[48:49], v[54:55], 1.0 op_sel_hi:[1,0]
	v_pk_add_f32 v[50:51], v[50:51], 1.0 op_sel_hi:[1,0]
	v_rcp_f32_e32 v48, v48
	v_rcp_f32_e32 v49, v49
	v_rcp_f32_e32 v50, v50
	v_rcp_f32_e32 v51, v51
	v_pk_mul_f32 v[44:45], v[44:45], v[48:49]
	v_pk_mul_f32 v[48:49], v[40:41], s[98:99] op_sel_hi:[1,0]
	v_pk_mul_f32 v[46:47], v[46:47], v[50:51]
	v_pk_mul_f32 v[50:51], v[42:43], s[98:99] op_sel_hi:[1,0]
	v_exp_f32_e32 v48, v48
	v_exp_f32_e32 v49, v49
	v_exp_f32_e32 v50, v50
	v_exp_f32_e32 v51, v51
	v_pk_add_f32 v[48:49], v[48:49], 1.0 op_sel_hi:[1,0]
	v_pk_add_f32 v[50:51], v[50:51], 1.0 op_sel_hi:[1,0]
	v_rcp_f32_e32 v48, v48
	v_rcp_f32_e32 v49, v49
	v_rcp_f32_e32 v50, v50
	v_rcp_f32_e32 v51, v51
	v_pk_mul_f32 v[36:37], v[44:45], v[36:37]
	v_pk_mul_f32 v[40:41], v[40:41], v[48:49]
	v_pk_mul_f32 v[38:39], v[46:47], v[38:39]
	v_pk_mul_f32 v[42:43], v[42:43], v[50:51]
	s_nop 0
	v_pk_mul_f32 v[42:43], v[42:43], v[34:35]
	v_pk_mul_f32 v[34:35], v[40:41], v[32:33]
	v_cvt_pk_bf16_f32 v32, v36, v37
	v_add_u32_e32 v36, 0x90, v150
	v_mad_i64_i32 v[36:37], s[20:21], v36, s42, v[112:113]
	v_cvt_pk_bf16_f32 v33, v38, v39
	v_cvt_pk_bf16_f32 v34, v34, v35
	v_cvt_pk_bf16_f32 v35, v42, v43
	v_lshl_add_u64 v[36:37], v[36:37], 0, v[114:115]
	v_pk_mul_f32 v[38:39], v[28:29], s[98:99] op_sel_hi:[1,0]
	global_store_dwordx4 v[36:37], v[32:35], off
	v_exp_f32_e32 v38, v38
	v_exp_f32_e32 v39, v39
	v_pk_mul_f32 v[34:35], v[30:31], s[98:99] op_sel_hi:[1,0]
	v_exp_f32_e32 v34, v34
	v_exp_f32_e32 v35, v35
	v_pk_add_f32 v[32:33], v[38:39], 1.0 op_sel_hi:[1,0]
	v_pk_add_f32 v[34:35], v[34:35], 1.0 op_sel_hi:[1,0]
	v_rcp_f32_e32 v32, v32
	v_rcp_f32_e32 v33, v33
	v_rcp_f32_e32 v34, v34
	v_rcp_f32_e32 v35, v35
	v_pk_mul_f32 v[28:29], v[28:29], v[32:33]
	v_pk_mul_f32 v[32:33], v[24:25], s[98:99] op_sel_hi:[1,0]
	v_pk_mul_f32 v[30:31], v[30:31], v[34:35]
	v_pk_mul_f32 v[34:35], v[26:27], s[98:99] op_sel_hi:[1,0]
	v_exp_f32_e32 v32, v32
	v_exp_f32_e32 v33, v33
	v_exp_f32_e32 v34, v34
	v_exp_f32_e32 v35, v35
	v_pk_add_f32 v[32:33], v[32:33], 1.0 op_sel_hi:[1,0]
	v_pk_add_f32 v[34:35], v[34:35], 1.0 op_sel_hi:[1,0]
	v_rcp_f32_e32 v32, v32
	v_rcp_f32_e32 v33, v33
	v_rcp_f32_e32 v34, v34
	v_rcp_f32_e32 v35, v35
	v_pk_mul_f32 v[20:21], v[28:29], v[20:21]
	v_pk_mul_f32 v[24:25], v[24:25], v[32:33]
	v_pk_mul_f32 v[22:23], v[30:31], v[22:23]
	v_pk_mul_f32 v[26:27], v[26:27], v[34:35]
	s_nop 0
	v_pk_mul_f32 v[26:27], v[26:27], v[18:19]
	v_pk_mul_f32 v[18:19], v[24:25], v[16:17]
	v_cvt_pk_bf16_f32 v16, v20, v21
	v_add_u32_e32 v20, 0xa0, v150
	v_mad_i64_i32 v[20:21], s[20:21], v20, s42, v[112:113]
	v_cvt_pk_bf16_f32 v17, v22, v23
	v_cvt_pk_bf16_f32 v18, v18, v19
	v_cvt_pk_bf16_f32 v19, v26, v27
	v_lshl_add_u64 v[20:21], v[20:21], 0, v[114:115]
	v_pk_mul_f32 v[22:23], v[12:13], s[98:99] op_sel_hi:[1,0]
	global_store_dwordx4 v[20:21], v[16:19], off
	v_exp_f32_e32 v22, v22
	v_exp_f32_e32 v23, v23
	v_pk_mul_f32 v[18:19], v[14:15], s[98:99] op_sel_hi:[1,0]
	v_exp_f32_e32 v18, v18
	v_exp_f32_e32 v19, v19
	v_pk_add_f32 v[16:17], v[22:23], 1.0 op_sel_hi:[1,0]
	v_pk_add_f32 v[18:19], v[18:19], 1.0 op_sel_hi:[1,0]
	v_rcp_f32_e32 v16, v16
	v_rcp_f32_e32 v17, v17
	v_rcp_f32_e32 v18, v18
	v_rcp_f32_e32 v19, v19
	v_pk_mul_f32 v[12:13], v[12:13], v[16:17]
	v_pk_mul_f32 v[16:17], v[8:9], s[98:99] op_sel_hi:[1,0]
	v_pk_mul_f32 v[14:15], v[14:15], v[18:19]
	v_pk_mul_f32 v[18:19], v[10:11], s[98:99] op_sel_hi:[1,0]
	v_exp_f32_e32 v16, v16
	v_exp_f32_e32 v17, v17
	v_exp_f32_e32 v18, v18
	v_exp_f32_e32 v19, v19
	v_pk_add_f32 v[16:17], v[16:17], 1.0 op_sel_hi:[1,0]
	v_pk_add_f32 v[18:19], v[18:19], 1.0 op_sel_hi:[1,0]
	v_rcp_f32_e32 v16, v16
	v_rcp_f32_e32 v17, v17
	v_rcp_f32_e32 v18, v18
	v_rcp_f32_e32 v19, v19
	v_pk_mul_f32 v[4:5], v[12:13], v[4:5]
	v_pk_mul_f32 v[8:9], v[8:9], v[16:17]
	v_pk_mul_f32 v[6:7], v[14:15], v[6:7]
	v_pk_mul_f32 v[10:11], v[10:11], v[18:19]
	s_nop 0
	v_pk_mul_f32 v[10:11], v[10:11], v[2:3]
	v_pk_mul_f32 v[2:3], v[8:9], v[0:1]
	v_cvt_pk_bf16_f32 v0, v4, v5
	v_add_u32_e32 v4, 0xb0, v150
	v_mad_i64_i32 v[4:5], s[20:21], v4, s42, v[112:113]
	v_lshl_add_u64 v[4:5], v[4:5], 0, v[114:115]
	v_cvt_pk_bf16_f32 v1, v6, v7
	v_cvt_pk_bf16_f32 v2, v2, v3
	v_cvt_pk_bf16_f32 v3, v10, v11
	global_store_dwordx4 v[4:5], v[0:3], off
	s_cbranch_vccnz .LBB0_233
	s_andn2_b64 vcc, exec, s[4:5]
	s_cbranch_vccnz .LBB0_232
	s_barrier
	s_branch .LBB0_232

.LBB0_510:
	s_ashr_i32 s4, s6, 3
	s_add_i32 s4, s8, s4
	s_mul_hi_i32 s5, s4, 0x3e0f83e1
	s_lshr_b32 s6, s5, 31
	s_ashr_i32 s5, s5, 6
	s_add_i32 s5, s5, s6
	s_lshl_b32 s6, s5, 3
	s_sub_i32 s7, 0x44, s6
	s_mulk_i32 s5, 0x108
	s_min_u32 s7, s7, 8
	s_sub_i32 s9, s4, s5
	s_sext_i32_i16 s4, s9
	v_cvt_f32_ubyte0_e32 v1, s7
	v_cvt_f32_i32_e32 v0, s4
	v_rcp_iflag_f32_e32 v2, v1
	s_ashr_i32 s4, s4, 30
	s_or_b32 s8, s4, 1
	v_mul_f32_e32 v2, v0, v2
	v_trunc_f32_e32 v2, v2
	v_fma_f32 v0, -v2, v1, v0
	v_cvt_i32_f32_e32 v2, v2
	v_cmp_ge_f32_e64 s[4:5], |v0|, v1
	s_and_b64 s[4:5], s[4:5], exec
	s_cselect_b32 s4, s8, 0
	v_readfirstlane_b32 s5, v2
	s_add_i32 s4, s5, s4
	s_sext_i32_i16 s8, s4
	s_mul_i32 s4, s4, s7
	s_sub_i32 s4, s9, s4
	s_sext_i32_i16 s4, s4
	s_add_i32 s6, s6, s4
	s_lshr_b32 s7, s6, 3
	s_mul_i32 s7, s7, 6
	s_mov_b32 s4, 0x10308100
	s_mov_b32 s5, 0x207185
	s_lshr_b64 s[4:5], s[4:5], s7
	s_and_b32 s7, s4, 63
	s_add_i32 s8, s8, s7
	s_cmp_gt_i32 s8, 32
	s_cselect_b32 s7, 33, 0
	s_sub_i32 s8, s8, s7

.LBB0_522:
	s_ashr_i32 s7, s7, 3
	s_add_i32 s7, s20, s7
	s_mul_hi_i32 s9, s7, 0x3e0f83e1
	s_lshr_b32 s18, s9, 31
	s_ashr_i32 s9, s9, 6
	s_add_i32 s9, s9, s18
	s_lshl_b32 s19, s9, 3
	s_sub_i32 s18, 0x44, s19
	s_min_i32 s20, s18, 8
	s_abs_i32 s18, s20
	v_cvt_f32_u32_e32 v0, s18
	s_sub_i32 s22, 0, s18
	s_mulk_i32 s9, 0x108
	s_sub_i32 s7, s7, s9
	v_rcp_iflag_f32_e32 v0, v0
	s_abs_i32 s9, s7
	s_xor_b32 s21, s7, s20
	s_ashr_i32 s21, s21, 31
	v_mul_f32_e32 v0, 0x4f7ffffe, v0
	v_cvt_u32_f32_e32 v0, v0
	s_nop 0
	v_readfirstlane_b32 s23, v0
	s_mul_i32 s22, s22, s23
	s_mul_hi_u32 s22, s23, s22
	s_add_i32 s23, s23, s22
	s_mul_hi_u32 s22, s9, s23
	s_mul_i32 s23, s22, s18
	s_sub_i32 s9, s9, s23
	s_add_i32 s24, s22, 1
	s_sub_i32 s23, s9, s18
	s_cmp_ge_u32 s9, s18
	s_cselect_b32 s22, s24, s22
	s_cselect_b32 s9, s23, s9
	s_add_i32 s23, s22, 1
	s_cmp_ge_u32 s9, s18
	s_cselect_b32 s9, s23, s22
	s_xor_b32 s9, s9, s21
	s_sub_i32 s18, s9, s21
	s_mul_i32 s9, s18, s20
	s_sub_i32 s7, s7, s9
	s_add_i32 s20, s19, s7
	s_lshr_b32 s9, s20, 3
	s_mul_i32 s9, s9, 6
	s_mov_b32 s22, 0x10308100
	s_mov_b32 s23, 0x207185
	s_lshr_b64 s[22:23], s[22:23], s9
	s_and_b32 s9, s22, 63
	s_add_i32 s18, s18, s9
	s_cmp_gt_i32 s18, 32
	s_cselect_b32 s9, 33, 0
	s_sub_i32 s18, s18, s9

.LBB0_1222:
	s_mov_b32 s98, 0xbfb8aa3b
	s_mov_b32 s99, 0xbfb8aa3b
	v_mul_f32_e32 v151, 0xbfb8aa3b, v124
	v_exp_f32_e32 v151, v151
	v_mul_f32_e32 v153, 0xbfb8aa3b, v125
	v_exp_f32_e32 v155, v153
	v_lshl_or_b32 v152, s43, 7, v146
	v_add_f32_e32 v151, 1.0, v151
	v_rcp_f32_e32 v154, v151
	v_add_f32_e32 v151, 1.0, v155
	v_mul_f32_e32 v155, 0xbfb8aa3b, v126
	v_exp_f32_e32 v156, v155
	v_mul_f32_e32 v155, 0xbfb8aa3b, v127
	v_exp_f32_e32 v157, v155
	v_rcp_f32_e32 v155, v151
	v_add_f32_e32 v151, 1.0, v156
	v_rcp_f32_e32 v156, v151
	v_add_f32_e32 v151, 1.0, v157
	v_rcp_f32_e32 v157, v151
	v_mul_f32_e32 v151, 0xbfb8aa3b, v120
	v_pk_mul_f32 v[124:125], v[124:125], v[154:155]
	v_exp_f32_e32 v151, v151
	v_mul_f32_e32 v154, 0xbfb8aa3b, v121
	v_exp_f32_e32 v155, v154
	v_pk_mul_f32 v[126:127], v[126:127], v[156:157]
	v_add_f32_e32 v151, 1.0, v151
	v_rcp_f32_e32 v154, v151
	v_add_f32_e32 v151, 1.0, v155
	v_mul_f32_e32 v155, 0xbfb8aa3b, v122
	v_exp_f32_e32 v156, v155
	v_mul_f32_e32 v155, 0xbfb8aa3b, v123
	v_exp_f32_e32 v157, v155
	v_rcp_f32_e32 v155, v151
	v_add_f32_e32 v151, 1.0, v156
	v_rcp_f32_e32 v156, v151
	v_add_f32_e32 v151, 1.0, v157
	v_rcp_f32_e32 v157, v151
	v_pk_mul_f32 v[120:121], v[120:121], v[154:155]
	v_pk_mul_f32 v[118:119], v[126:127], v[118:119]
	v_pk_mul_f32 v[116:117], v[124:125], v[116:117]
	v_pk_mul_f32 v[122:123], v[122:123], v[156:157]
	v_pk_mul_f32 v[112:113], v[120:121], v[112:113]
	v_lshl_add_u32 v150, s20, 8, v144
	v_ashrrev_i32_e32 v153, 31, v152
	v_pk_mul_f32 v[114:115], v[122:123], v[114:115]
	v_cvt_pk_bf16_f32 v116, v116, v117
	v_cvt_pk_bf16_f32 v117, v118, v119
	v_cvt_pk_bf16_f32 v118, v112, v113
	v_mov_b64_e32 v[112:113], s[80:81]
	v_cvt_pk_bf16_f32 v119, v114, v115
	v_mad_i64_i32 v[120:121], s[22:23], v150, s42, v[112:113]
	v_lshlrev_b64 v[114:115], 1, v[152:153]
	v_lshl_add_u64 v[120:121], v[120:121], 0, v[114:115]
	v_pk_mul_f32 v[122:123], v[108:109], s[98:99] op_sel_hi:[1,0]
	global_store_dwordx4 v[120:121], v[116:119], off
	v_exp_f32_e32 v122, v122
	v_exp_f32_e32 v123, v123
	v_pk_mul_f32 v[118:119], v[110:111], s[98:99] op_sel_hi:[1,0]
	v_exp_f32_e32 v118, v118
	v_exp_f32_e32 v119, v119
	v_pk_add_f32 v[116:117], v[122:123], 1.0 op_sel_hi:[1,0]
	v_pk_add_f32 v[118:119], v[118:119], 1.0 op_sel_hi:[1,0]
	v_rcp_f32_e32 v116, v116
	v_rcp_f32_e32 v117, v117
	v_rcp_f32_e32 v118, v118
	v_rcp_f32_e32 v119, v119
	s_andn2_b64 vcc, exec, s[2:3]
	v_pk_mul_f32 v[108:109], v[108:109], v[116:117]
	v_pk_mul_f32 v[116:117], v[104:105], s[98:99] op_sel_hi:[1,0]
	v_pk_mul_f32 v[110:111], v[110:111], v[118:119]
	v_pk_mul_f32 v[118:119], v[106:107], s[98:99] op_sel_hi:[1,0]
	v_exp_f32_e32 v116, v116
	v_exp_f32_e32 v117, v117
	v_exp_f32_e32 v118, v118
	v_exp_f32_e32 v119, v119
	v_pk_add_f32 v[116:117], v[116:117], 1.0 op_sel_hi:[1,0]
	v_pk_add_f32 v[118:119], v[118:119], 1.0 op_sel_hi:[1,0]
	v_rcp_f32_e32 v116, v116
	v_rcp_f32_e32 v117, v117
	v_rcp_f32_e32 v118, v118
	v_rcp_f32_e32 v119, v119
	v_pk_mul_f32 v[100:101], v[108:109], v[100:101]
	v_pk_mul_f32 v[104:105], v[104:105], v[116:117]
	v_pk_mul_f32 v[102:103], v[110:111], v[102:103]
	v_pk_mul_f32 v[106:107], v[106:107], v[118:119]
	s_mov_b64 s[2:3], -1
	v_pk_mul_f32 v[106:107], v[106:107], v[98:99]
	v_pk_mul_f32 v[98:99], v[104:105], v[96:97]
	v_cvt_pk_bf16_f32 v96, v100, v101
	v_or_b32_e32 v100, 16, v150
	v_mad_i64_i32 v[100:101], s[22:23], v100, s42, v[112:113]
	v_cvt_pk_bf16_f32 v97, v102, v103
	v_cvt_pk_bf16_f32 v98, v98, v99
	v_cvt_pk_bf16_f32 v99, v106, v107
	v_lshl_add_u64 v[100:101], v[100:101], 0, v[114:115]
	v_pk_mul_f32 v[102:103], v[92:93], s[98:99] op_sel_hi:[1,0]
	global_store_dwordx4 v[100:101], v[96:99], off
	v_exp_f32_e32 v102, v102
	v_exp_f32_e32 v103, v103
	v_pk_mul_f32 v[98:99], v[94:95], s[98:99] op_sel_hi:[1,0]
	v_exp_f32_e32 v98, v98
	v_exp_f32_e32 v99, v99
	v_pk_add_f32 v[96:97], v[102:103], 1.0 op_sel_hi:[1,0]
	v_pk_add_f32 v[98:99], v[98:99], 1.0 op_sel_hi:[1,0]
	v_rcp_f32_e32 v96, v96
	v_rcp_f32_e32 v97, v97
	v_rcp_f32_e32 v98, v98
	v_rcp_f32_e32 v99, v99
	v_pk_mul_f32 v[92:93], v[92:93], v[96:97]
	v_pk_mul_f32 v[96:97], v[88:89], s[98:99] op_sel_hi:[1,0]
	v_pk_mul_f32 v[94:95], v[94:95], v[98:99]
	v_pk_mul_f32 v[98:99], v[90:91], s[98:99] op_sel_hi:[1,0]
	v_exp_f32_e32 v96, v96
	v_exp_f32_e32 v97, v97
	v_exp_f32_e32 v98, v98
	v_exp_f32_e32 v99, v99
	v_pk_add_f32 v[96:97], v[96:97], 1.0 op_sel_hi:[1,0]
	v_pk_add_f32 v[98:99], v[98:99], 1.0 op_sel_hi:[1,0]
	v_rcp_f32_e32 v96, v96
	v_rcp_f32_e32 v97, v97
	v_rcp_f32_e32 v98, v98
	v_rcp_f32_e32 v99, v99
	v_pk_mul_f32 v[84:85], v[92:93], v[84:85]
	v_pk_mul_f32 v[88:89], v[88:89], v[96:97]
	v_pk_mul_f32 v[86:87], v[94:95], v[86:87]
	v_pk_mul_f32 v[90:91], v[90:91], v[98:99]
	s_nop 0
	v_pk_mul_f32 v[90:91], v[90:91], v[82:83]
	v_pk_mul_f32 v[82:83], v[88:89], v[80:81]
	v_cvt_pk_bf16_f32 v80, v84, v85
	v_or_b32_e32 v84, 32, v150
	v_mad_i64_i32 v[84:85], s[22:23], v84, s42, v[112:113]
	v_cvt_pk_bf16_f32 v81, v86, v87
	v_cvt_pk_bf16_f32 v82, v82, v83
	v_cvt_pk_bf16_f32 v83, v90, v91
	v_lshl_add_u64 v[84:85], v[84:85], 0, v[114:115]
	v_pk_mul_f32 v[86:87], v[76:77], s[98:99] op_sel_hi:[1,0]
	global_store_dwordx4 v[84:85], v[80:83], off
	v_exp_f32_e32 v86, v86
	v_exp_f32_e32 v87, v87
	v_pk_mul_f32 v[82:83], v[78:79], s[98:99] op_sel_hi:[1,0]
	v_exp_f32_e32 v82, v82
	v_exp_f32_e32 v83, v83
	v_pk_add_f32 v[80:81], v[86:87], 1.0 op_sel_hi:[1,0]
	v_pk_add_f32 v[82:83], v[82:83], 1.0 op_sel_hi:[1,0]
	v_rcp_f32_e32 v80, v80
	v_rcp_f32_e32 v81, v81
	v_rcp_f32_e32 v82, v82
	v_rcp_f32_e32 v83, v83
	v_pk_mul_f32 v[76:77], v[76:77], v[80:81]
	v_pk_mul_f32 v[80:81], v[72:73], s[98:99] op_sel_hi:[1,0]
	v_pk_mul_f32 v[78:79], v[78:79], v[82:83]
	v_pk_mul_f32 v[82:83], v[74:75], s[98:99] op_sel_hi:[1,0]
	v_exp_f32_e32 v80, v80
	v_exp_f32_e32 v81, v81
	v_exp_f32_e32 v82, v82
	v_exp_f32_e32 v83, v83
	v_pk_add_f32 v[80:81], v[80:81], 1.0 op_sel_hi:[1,0]
	v_pk_add_f32 v[82:83], v[82:83], 1.0 op_sel_hi:[1,0]
	v_rcp_f32_e32 v80, v80
	v_rcp_f32_e32 v81, v81
	v_rcp_f32_e32 v82, v82
	v_rcp_f32_e32 v83, v83
	v_pk_mul_f32 v[68:69], v[76:77], v[68:69]
	v_pk_mul_f32 v[72:73], v[72:73], v[80:81]
	v_pk_mul_f32 v[70:71], v[78:79], v[70:71]
	v_pk_mul_f32 v[74:75], v[74:75], v[82:83]
	s_nop 0
	v_pk_mul_f32 v[74:75], v[74:75], v[66:67]
	v_pk_mul_f32 v[66:67], v[72:73], v[64:65]
	v_cvt_pk_bf16_f32 v64, v68, v69
	v_or_b32_e32 v68, 48, v150
	v_mad_i64_i32 v[68:69], s[22:23], v68, s42, v[112:113]
	v_cvt_pk_bf16_f32 v65, v70, v71
	v_cvt_pk_bf16_f32 v66, v66, v67
	v_cvt_pk_bf16_f32 v67, v74, v75
	v_lshl_add_u64 v[68:69], v[68:69], 0, v[114:115]
	global_store_dwordx4 v[68:69], v[64:67], off
	v_add_u32_e32 v68, 0x80, v150
	s_nop 0
	v_pk_mul_f32 v[64:65], v[60:61], s[98:99] op_sel_hi:[1,0]
	v_pk_mul_f32 v[66:67], v[62:63], s[98:99] op_sel_hi:[1,0]
	v_exp_f32_e32 v64, v64
	v_exp_f32_e32 v65, v65
	v_exp_f32_e32 v66, v66
	v_exp_f32_e32 v67, v67
	v_pk_add_f32 v[64:65], v[64:65], 1.0 op_sel_hi:[1,0]
	v_pk_add_f32 v[66:67], v[66:67], 1.0 op_sel_hi:[1,0]
	v_rcp_f32_e32 v64, v64
	v_rcp_f32_e32 v65, v65
	v_rcp_f32_e32 v66, v66
	v_rcp_f32_e32 v67, v67
	v_pk_mul_f32 v[60:61], v[60:61], v[64:65]
	v_pk_mul_f32 v[64:65], v[56:57], s[98:99] op_sel_hi:[1,0]
	v_pk_mul_f32 v[62:63], v[62:63], v[66:67]
	v_pk_mul_f32 v[66:67], v[58:59], s[98:99] op_sel_hi:[1,0]
	v_exp_f32_e32 v64, v64
	v_exp_f32_e32 v65, v65
	v_exp_f32_e32 v66, v66
	v_exp_f32_e32 v67, v67
	v_pk_add_f32 v[64:65], v[64:65], 1.0 op_sel_hi:[1,0]
	v_pk_add_f32 v[66:67], v[66:67], 1.0 op_sel_hi:[1,0]
	v_rcp_f32_e32 v64, v64
	v_rcp_f32_e32 v65, v65
	v_rcp_f32_e32 v66, v66
	v_rcp_f32_e32 v67, v67
	v_pk_mul_f32 v[52:53], v[60:61], v[52:53]
	v_pk_mul_f32 v[56:57], v[56:57], v[64:65]
	v_pk_mul_f32 v[54:55], v[62:63], v[54:55]
	v_pk_mul_f32 v[58:59], v[58:59], v[66:67]
	s_nop 0
	v_pk_mul_f32 v[58:59], v[58:59], v[50:51]
	v_pk_mul_f32 v[50:51], v[56:57], v[48:49]
	v_cvt_pk_bf16_f32 v48, v52, v53
	v_mad_i64_i32 v[52:53], s[22:23], v68, s42, v[112:113]
	v_cvt_pk_bf16_f32 v49, v54, v55
	v_cvt_pk_bf16_f32 v50, v50, v51
	v_cvt_pk_bf16_f32 v51, v58, v59
	v_lshl_add_u64 v[52:53], v[52:53], 0, v[114:115]
	v_pk_mul_f32 v[54:55], v[44:45], s[98:99] op_sel_hi:[1,0]
	global_store_dwordx4 v[52:53], v[48:51], off
	v_exp_f32_e32 v54, v54
	v_exp_f32_e32 v55, v55
	v_pk_mul_f32 v[50:51], v[46:47], s[98:99] op_sel_hi:[1,0]
	v_exp_f32_e32 v50, v50
	v_exp_f32_e32 v51, v51
	v_pk_add_f32 v[48:49], v[54:55], 1.0 op_sel_hi:[1,0]
	v_pk_add_f32 v[50:51], v[50:51], 1.0 op_sel_hi:[1,0]
	v_rcp_f32_e32 v48, v48
	v_rcp_f32_e32 v49, v49
	v_rcp_f32_e32 v50, v50
	v_rcp_f32_e32 v51, v51
	v_pk_mul_f32 v[44:45], v[44:45], v[48:49]
	v_pk_mul_f32 v[48:49], v[40:41], s[98:99] op_sel_hi:[1,0]
	v_pk_mul_f32 v[46:47], v[46:47], v[50:51]
	v_pk_mul_f32 v[50:51], v[42:43], s[98:99] op_sel_hi:[1,0]
	v_exp_f32_e32 v48, v48
	v_exp_f32_e32 v49, v49
	v_exp_f32_e32 v50, v50
	v_exp_f32_e32 v51, v51
	v_pk_add_f32 v[48:49], v[48:49], 1.0 op_sel_hi:[1,0]
	v_pk_add_f32 v[50:51], v[50:51], 1.0 op_sel_hi:[1,0]
	v_rcp_f32_e32 v48, v48
	v_rcp_f32_e32 v49, v49
	v_rcp_f32_e32 v50, v50
	v_rcp_f32_e32 v51, v51
	v_pk_mul_f32 v[36:37], v[44:45], v[36:37]
	v_pk_mul_f32 v[40:41], v[40:41], v[48:49]
	v_pk_mul_f32 v[38:39], v[46:47], v[38:39]
	v_pk_mul_f32 v[42:43], v[42:43], v[50:51]
	s_nop 0
	v_pk_mul_f32 v[42:43], v[42:43], v[34:35]
	v_pk_mul_f32 v[34:35], v[40:41], v[32:33]
	v_cvt_pk_bf16_f32 v32, v36, v37
	v_add_u32_e32 v36, 0x90, v150
	v_mad_i64_i32 v[36:37], s[22:23], v36, s42, v[112:113]
	v_cvt_pk_bf16_f32 v33, v38, v39
	v_cvt_pk_bf16_f32 v34, v34, v35
	v_cvt_pk_bf16_f32 v35, v42, v43
	v_lshl_add_u64 v[36:37], v[36:37], 0, v[114:115]
	v_pk_mul_f32 v[38:39], v[28:29], s[98:99] op_sel_hi:[1,0]
	global_store_dwordx4 v[36:37], v[32:35], off
	v_exp_f32_e32 v38, v38
	v_exp_f32_e32 v39, v39
	v_pk_mul_f32 v[34:35], v[30:31], s[98:99] op_sel_hi:[1,0]
	v_exp_f32_e32 v34, v34
	v_exp_f32_e32 v35, v35
	v_pk_add_f32 v[32:33], v[38:39], 1.0 op_sel_hi:[1,0]
	v_pk_add_f32 v[34:35], v[34:35], 1.0 op_sel_hi:[1,0]
	v_rcp_f32_e32 v32, v32
	v_rcp_f32_e32 v33, v33
	v_rcp_f32_e32 v34, v34
	v_rcp_f32_e32 v35, v35
	v_pk_mul_f32 v[28:29], v[28:29], v[32:33]
	v_pk_mul_f32 v[32:33], v[24:25], s[98:99] op_sel_hi:[1,0]
	v_pk_mul_f32 v[30:31], v[30:31], v[34:35]
	v_pk_mul_f32 v[34:35], v[26:27], s[98:99] op_sel_hi:[1,0]
	v_exp_f32_e32 v32, v32
	v_exp_f32_e32 v33, v33
	v_exp_f32_e32 v34, v34
	v_exp_f32_e32 v35, v35
	v_pk_add_f32 v[32:33], v[32:33], 1.0 op_sel_hi:[1,0]
	v_pk_add_f32 v[34:35], v[34:35], 1.0 op_sel_hi:[1,0]
	v_rcp_f32_e32 v32, v32
	v_rcp_f32_e32 v33, v33
	v_rcp_f32_e32 v34, v34
	v_rcp_f32_e32 v35, v35
	v_pk_mul_f32 v[20:21], v[28:29], v[20:21]
	v_pk_mul_f32 v[24:25], v[24:25], v[32:33]
	v_pk_mul_f32 v[22:23], v[30:31], v[22:23]
	v_pk_mul_f32 v[26:27], v[26:27], v[34:35]
	s_nop 0
	v_pk_mul_f32 v[26:27], v[26:27], v[18:19]
	v_pk_mul_f32 v[18:19], v[24:25], v[16:17]
	v_cvt_pk_bf16_f32 v16, v20, v21
	v_add_u32_e32 v20, 0xa0, v150
	v_mad_i64_i32 v[20:21], s[22:23], v20, s42, v[112:113]
	v_cvt_pk_bf16_f32 v17, v22, v23
	v_cvt_pk_bf16_f32 v18, v18, v19
	v_cvt_pk_bf16_f32 v19, v26, v27
	v_lshl_add_u64 v[20:21], v[20:21], 0, v[114:115]
	v_pk_mul_f32 v[22:23], v[12:13], s[98:99] op_sel_hi:[1,0]
	global_store_dwordx4 v[20:21], v[16:19], off
	v_exp_f32_e32 v22, v22
	v_exp_f32_e32 v23, v23
	v_pk_mul_f32 v[18:19], v[14:15], s[98:99] op_sel_hi:[1,0]
	v_exp_f32_e32 v18, v18
	v_exp_f32_e32 v19, v19
	v_pk_add_f32 v[16:17], v[22:23], 1.0 op_sel_hi:[1,0]
	v_pk_add_f32 v[18:19], v[18:19], 1.0 op_sel_hi:[1,0]
	v_rcp_f32_e32 v16, v16
	v_rcp_f32_e32 v17, v17
	v_rcp_f32_e32 v18, v18
	v_rcp_f32_e32 v19, v19
	v_pk_mul_f32 v[12:13], v[12:13], v[16:17]
	v_pk_mul_f32 v[16:17], v[8:9], s[98:99] op_sel_hi:[1,0]
	v_pk_mul_f32 v[14:15], v[14:15], v[18:19]
	v_pk_mul_f32 v[18:19], v[10:11], s[98:99] op_sel_hi:[1,0]
	v_exp_f32_e32 v16, v16
	v_exp_f32_e32 v17, v17
	v_exp_f32_e32 v18, v18
	v_exp_f32_e32 v19, v19
	v_pk_add_f32 v[16:17], v[16:17], 1.0 op_sel_hi:[1,0]
	v_pk_add_f32 v[18:19], v[18:19], 1.0 op_sel_hi:[1,0]
	v_rcp_f32_e32 v16, v16
	v_rcp_f32_e32 v17, v17
	v_rcp_f32_e32 v18, v18
	v_rcp_f32_e32 v19, v19
	v_pk_mul_f32 v[4:5], v[12:13], v[4:5]
	v_pk_mul_f32 v[8:9], v[8:9], v[16:17]
	v_pk_mul_f32 v[6:7], v[14:15], v[6:7]
	v_pk_mul_f32 v[10:11], v[10:11], v[18:19]
	s_nop 0
	v_pk_mul_f32 v[10:11], v[10:11], v[2:3]
	v_pk_mul_f32 v[2:3], v[8:9], v[0:1]
	v_cvt_pk_bf16_f32 v0, v4, v5
	v_add_u32_e32 v4, 0xb0, v150
	v_mad_i64_i32 v[4:5], s[22:23], v4, s42, v[112:113]
	v_lshl_add_u64 v[4:5], v[4:5], 0, v[114:115]
	v_cvt_pk_bf16_f32 v1, v6, v7
	v_cvt_pk_bf16_f32 v2, v2, v3
	v_cvt_pk_bf16_f32 v3, v10, v11
	global_store_dwordx4 v[4:5], v[0:3], off
	s_cbranch_vccnz .LBB0_1215
	s_andn2_b64 vcc, exec, s[6:7]
	s_cbranch_vccnz .LBB0_1214
	s_barrier
	s_branch .LBB0_1214
